# final1: opt14 + conv-weight loads hoisted above the halo barrier in the gate/up GEMM epilogue
# speedup vs baseline: 1.0061x; 1.0061x over previous
; #define PG8_STAGE(bufoff, gbase, voff) do { _Pragma("unroll") for (int _i = 0; _i < 2; ++_i) \
;         __builtin_amdgcn_global_load_lds((const unsigned*)((const char*)(gbase) + (voff)[_i]), (PG8_LAS unsigned*)(lds + (bufoff) + ldsw + _i * 8192), 16, 0, 0); } while (0)
; #define PG8_LDA(dst, b, h) do { _Pragma("unroll") for (int m = 0; m < 4; ++m) _Pragma("unroll") for (int k = 0; k < 2; ++k) dst[m][k] = *(const PG8_LAS half8*)(lds + PG8_SA(b, h) + aoff + m * 2048 + k * 1024); } while (0)
; #define PG8_LDB(dst, b, h) do { _Pragma("unroll") for (int n = 0; n < 2; ++n) _Pragma("unroll") for (int k = 0; k < 2; ++k) dst[n][k] = *(const PG8_LAS half8*)(lds + PG8_SB(b, h) + boff + n * 2048 + k * 1024); } while (0)
; #define PG8_WAIT_V(n) asm volatile("s_waitcnt vmcnt(" #n ")" ::: "memory")
; #define PG8_BAR __builtin_amdgcn_s_barrier()
; template <class Epi>
; __device__ __forceinline__ void gemm_phase(PG8_LAS unsigned char* lds, const Gemm g, const StaticOrder& S_, const Epi& E) {
;     ...
;         for (int t = 0; t < nt; t += 2) {
;             const bool last = (t == nt - 2);
;             const char* a1 = cA + (size_t)(t + 1) * kstep;
;             const char* a2 = last ? nA : cA + (size_t)(t + 2) * kstep; const char* b2 = last ? nB : cB + (size_t)(t + 2) * kstep;
;             const char* a3 = a2 + kstep; const char* b3 = b2 + kstep;
;             PG8_LDB(B0, 0, 0); PG8_LDB(B1, 0, 1); PG8_SCHED; PG8_LDA(At, 0, 0); PG8_STAGE(PG8_SA(1, 1), a1 + hstepA, voffA);
;             PG8_WAIT_V(8); PG8_WAIT_L(0); PG8_BAR; PG8_MMA(0, 0, At, B0); PG8_MMA(0, 1, At, B1); PG8_BAR; PG8_SCHED;
;             PG8_LDA(At, 0, 1); PG8_STAGE(PG8_SB(0, 0), b2, voffB); PG8_STAGE(PG8_SB(0, 1), b2 + hstepB, voffB); PG8_STAGE(PG8_SA(0, 0), a2, voffA);
;             PG8_WAIT_V(8); PG8_WAIT_L(0); PG8_BAR; PG8_MMA(1, 0, At, B0); PG8_MMA(1, 1, At, B1); PG8_BAR; PG8_SCHED;
;             PG8_LDB(B0, 1, 0); PG8_LDB(B1, 1, 1); PG8_SCHED; PG8_LDA(At, 1, 0); PG8_STAGE(PG8_SA(0, 1), a2 + hstepA, voffA);
;             PG8_WAIT_V(8); PG8_WAIT_L(0); PG8_BAR; PG8_MMA(0, 0, At, B0); PG8_MMA(0, 1, At, B1); PG8_BAR; PG8_SCHED;
;             PG8_LDA(At, 1, 1); PG8_STAGE(PG8_SB(1, 0), b3, voffB); PG8_STAGE(PG8_SB(1, 1), b3 + hstepB, voffB); PG8_STAGE(PG8_SA(1, 0), a3, voffA);
;             PG8_WAIT_V(8); PG8_WAIT_L(0); PG8_BAR; PG8_MMA(1, 0, At, B0); PG8_MMA(1, 1, At, B1); PG8_BAR; PG8_SCHED;
.LBB0_1307:
	s_add_u32 s2, s56, 0xfffc0080
	s_addc_u32 s3, s57, -1
	s_add_i32 s33, 0, 0x10000
	s_cmp_eq_u32 s88, 12
	s_cselect_b32 s59, s47, s3
	s_cselect_b32 s58, s53, s2
	s_cselect_b32 s3, s45, s84
	s_cselect_b32 s2, s55, s83
	s_add_i32 s94, 0, 0x14000
	v_add_u32_e32 v78, s33, v208
	v_add_u32_e32 v94, s94, v208
	ds_read_b128 v[66:69], v78
	ds_read_b128 v[70:73], v78 offset:1024
	ds_read_b128 v[74:77], v78 offset:2048
	ds_read_b128 v[78:81], v78 offset:3072
	ds_read_b128 v[82:85], v94
	ds_read_b128 v[86:89], v94 offset:1024
	ds_read_b128 v[90:93], v94 offset:2048
	ds_read_b128 v[94:97], v94 offset:3072
	v_lshl_add_u64 v[242:243], s[56:57], 0, v[192:193]
	s_add_i32 m0, s72, 0xc000
	ds_read_b128 v[162:165], v220
	ds_read_b128 v[166:169], v220 offset:1024
	ds_read_b128 v[194:197], v220 offset:2048
	ds_read_b128 v[222:225], v220 offset:3072
	ds_read_b128 v[226:229], v220 offset:4096
	ds_read_b128 v[230:233], v220 offset:5120
	ds_read_b128 v[234:237], v220 offset:6144
	ds_read_b128 v[238:241], v220 offset:7168
	global_load_lds_dwordx4 v[242:243], off
	v_lshl_add_u64 v[242:243], s[56:57], 0, v[190:191]
	s_add_i32 m0, s72, 0xe000
	s_nop 0
	global_load_lds_dwordx4 v[242:243], off
	s_waitcnt vmcnt(8)
	s_waitcnt lgkmcnt(0)
	s_barrier
	s_setprio 1
	s_waitcnt lgkmcnt(0)
	v_mfma_f32_16x16x32_f16 v[158:161], v[66:69], v[162:165], v[158:161]
	v_mfma_f32_16x16x32_f16 v[154:157], v[74:77], v[162:165], v[154:157]
	v_mfma_f32_16x16x32_f16 v[142:145], v[66:69], v[194:197], v[142:145]
	v_mfma_f32_16x16x32_f16 v[134:137], v[74:77], v[194:197], v[134:137]
	v_mfma_f32_16x16x32_f16 v[126:129], v[66:69], v[226:229], v[126:129]
	v_mfma_f32_16x16x32_f16 v[118:121], v[74:77], v[226:229], v[118:121]
	v_mfma_f32_16x16x32_f16 v[106:109], v[66:69], v[234:237], v[106:109]
	v_mfma_f32_16x16x32_f16 v[102:105], v[74:77], v[234:237], v[102:105]
	v_mfma_f32_16x16x32_f16 v[158:161], v[70:73], v[166:169], v[158:161]
	v_mfma_f32_16x16x32_f16 v[154:157], v[78:81], v[166:169], v[154:157]
	v_mfma_f32_16x16x32_f16 v[142:145], v[70:73], v[222:225], v[142:145]
	v_mfma_f32_16x16x32_f16 v[134:137], v[78:81], v[222:225], v[134:137]
	v_mfma_f32_16x16x32_f16 v[126:129], v[70:73], v[230:233], v[126:129]
	v_mfma_f32_16x16x32_f16 v[118:121], v[78:81], v[230:233], v[118:121]
	v_mfma_f32_16x16x32_f16 v[106:109], v[70:73], v[238:241], v[106:109]
	v_mfma_f32_16x16x32_f16 v[102:105], v[78:81], v[238:241], v[102:105]
	s_setprio 0
	s_setprio 1
	v_mfma_f32_16x16x32_f16 v[150:153], v[82:85], v[162:165], v[150:153]
	v_mfma_f32_16x16x32_f16 v[146:149], v[90:93], v[162:165], v[146:149]
	v_mfma_f32_16x16x32_f16 v[138:141], v[82:85], v[194:197], v[138:141]
	v_mfma_f32_16x16x32_f16 v[130:133], v[90:93], v[194:197], v[130:133]
	v_mfma_f32_16x16x32_f16 v[122:125], v[82:85], v[226:229], v[122:125]
	v_mfma_f32_16x16x32_f16 v[114:117], v[90:93], v[226:229], v[114:117]
	v_mfma_f32_16x16x32_f16 v[110:113], v[82:85], v[234:237], v[110:113]
	v_mfma_f32_16x16x32_f16 v[98:101], v[90:93], v[234:237], v[98:101]
	v_mfma_f32_16x16x32_f16 v[150:153], v[86:89], v[166:169], v[150:153]
	v_mfma_f32_16x16x32_f16 v[146:149], v[94:97], v[166:169], v[146:149]
	v_mfma_f32_16x16x32_f16 v[138:141], v[86:89], v[222:225], v[138:141]
	v_mfma_f32_16x16x32_f16 v[130:133], v[94:97], v[222:225], v[130:133]
	v_mfma_f32_16x16x32_f16 v[122:125], v[86:89], v[230:233], v[122:125]
	v_mfma_f32_16x16x32_f16 v[114:117], v[94:97], v[230:233], v[114:117]
	v_mfma_f32_16x16x32_f16 v[110:113], v[86:89], v[238:241], v[110:113]
	v_mfma_f32_16x16x32_f16 v[98:101], v[94:97], v[238:241], v[98:101]
	s_setprio 0
	s_barrier
	s_add_i32 s33, s33, s71
	v_lshl_add_u64 v[242:243], s[2:3], 0, v[0:1]
	s_mov_b32 m0, s33
	ds_read_b128 v[162:165], v220 offset:16384
	ds_read_b128 v[166:169], v220 offset:17408
	ds_read_b128 v[194:197], v220 offset:18432
	ds_read_b128 v[222:225], v220 offset:19456
	ds_read_b128 v[226:229], v220 offset:20480
	ds_read_b128 v[230:233], v220 offset:21504
	ds_read_b128 v[234:237], v220 offset:22528
	ds_read_b128 v[238:241], v220 offset:23552
	global_load_lds_dwordx4 v[242:243], off
	s_add_i32 m0, s33, 0x2000
	s_add_u32 s92, s2, 0x40000
	v_lshl_add_u64 v[244:245], s[2:3], 0, v[184:185]
	s_addc_u32 s93, s3, 0
	s_add_i32 s33, s94, s71
	global_load_lds_dwordx4 v[244:245], off
	v_lshl_add_u64 v[246:247], s[92:93], 0, v[0:1]
	s_mov_b32 m0, s33
	v_lshl_add_u64 v[248:249], s[58:59], 0, v[182:183]
	global_load_lds_dwordx4 v[246:247], off
	v_lshl_add_u64 v[246:247], s[92:93], 0, v[184:185]
	s_add_i32 m0, s33, 0x2000
	s_nop 0
	global_load_lds_dwordx4 v[246:247], off
	v_lshl_add_u64 v[246:247], s[58:59], 0, v[180:181]
	s_mov_b32 m0, s72
	s_nop 0
	global_load_lds_dwordx4 v[246:247], off
	s_mov_b32 m0, s73
	s_nop 0
	global_load_lds_dwordx4 v[248:249], off
	s_waitcnt vmcnt(8)
	s_waitcnt lgkmcnt(0)
	s_barrier
; #define PG8_STAGE(bufoff, gbase, voff) do { _Pragma("unroll") for (int _i = 0; _i < 2; ++_i) \
;         __builtin_amdgcn_global_load_lds((const unsigned*)((const char*)(gbase) + (voff)[_i]), (PG8_LAS unsigned*)(lds + (bufoff) + ldsw + _i * 8192), 16, 0, 0); } while (0)
; #define PG8_LDA(dst, b, h) do { _Pragma("unroll") for (int m = 0; m < 4; ++m) _Pragma("unroll") for (int k = 0; k < 2; ++k) dst[m][k] = *(const PG8_LAS half8*)(lds + PG8_SA(b, h) + aoff + m * 2048 + k * 1024); } while (0)
; #define PG8_LDB(dst, b, h) do { _Pragma("unroll") for (int n = 0; n < 2; ++n) _Pragma("unroll") for (int k = 0; k < 2; ++k) dst[n][k] = *(const PG8_LAS half8*)(lds + PG8_SB(b, h) + boff + n * 2048 + k * 1024); } while (0)
; #define PG8_MMA(ai, bj, At, Bt) do { __builtin_amdgcn_s_setprio(1); _Pragma("unroll") for (int m = 0; m < 4; ++m) _Pragma("unroll") for (int n = 0; n < 2; ++n) _Pragma("unroll") for (int k = 0; k < 2; ++k) \
;         acc[ai][bj][m][n] = __builtin_amdgcn_mfma_f32_16x16x32_f16(Bt[n][k], At[m][k], acc[ai][bj][m][n], 0, 0, 0); __builtin_amdgcn_s_setprio(0); } while (0)
; #define PG8_WAIT_V(n) asm volatile("s_waitcnt vmcnt(" #n ")" ::: "memory")
; #define PG8_BAR __builtin_amdgcn_s_barrier()
; template <class Epi>
; __device__ __forceinline__ void gemm_phase(PG8_LAS unsigned char* lds, const Gemm g, const StaticOrder& S_, const Epi& E) {
;     ...
;             PG8_LDB(B0, 0, 0); PG8_LDB(B1, 0, 1); PG8_SCHED; PG8_LDA(At, 0, 0); PG8_STAGE(PG8_SA(1, 1), a1 + hstepA, voffA);
;             PG8_WAIT_V(8); PG8_WAIT_L(0); PG8_BAR; PG8_MMA(0, 0, At, B0); PG8_MMA(0, 1, At, B1); PG8_BAR; PG8_SCHED;
;             PG8_LDA(At, 0, 1); PG8_STAGE(PG8_SB(0, 0), b2, voffB); PG8_STAGE(PG8_SB(0, 1), b2 + hstepB, voffB); PG8_STAGE(PG8_SA(0, 0), a2, voffA);
;             PG8_WAIT_V(8); PG8_WAIT_L(0); PG8_BAR; PG8_MMA(1, 0, At, B0); PG8_MMA(1, 1, At, B1); PG8_BAR; PG8_SCHED;
;             PG8_LDB(B0, 1, 0); PG8_LDB(B1, 1, 1); PG8_SCHED; PG8_LDA(At, 1, 0); PG8_STAGE(PG8_SA(0, 1), a2 + hstepA, voffA);
;             PG8_WAIT_V(8); PG8_WAIT_L(0); PG8_BAR; PG8_MMA(0, 0, At, B0); PG8_MMA(0, 1, At, B1); PG8_BAR; PG8_SCHED;
;             PG8_LDA(At, 1, 1); PG8_STAGE(PG8_SB(1, 0), b3, voffB); PG8_STAGE(PG8_SB(1, 1), b3 + hstepB, voffB); PG8_STAGE(PG8_SA(1, 0), a3, voffA);
;             PG8_WAIT_V(8); PG8_WAIT_L(0); PG8_BAR; PG8_MMA(1, 0, At, B0); PG8_MMA(1, 1, At, B1); PG8_BAR; PG8_SCHED;
	s_setprio 1
	s_waitcnt lgkmcnt(0)
	v_mfma_f32_16x16x32_f16 v[62:65], v[66:69], v[162:165], v[62:65]
	v_mfma_f32_16x16x32_f16 v[58:61], v[74:77], v[162:165], v[58:61]
	v_mfma_f32_16x16x32_f16 v[46:49], v[66:69], v[194:197], v[46:49]
	v_mfma_f32_16x16x32_f16 v[38:41], v[74:77], v[194:197], v[38:41]
	v_mfma_f32_16x16x32_f16 v[30:33], v[66:69], v[226:229], v[30:33]
	v_mfma_f32_16x16x32_f16 v[22:25], v[74:77], v[226:229], v[22:25]
	v_mfma_f32_16x16x32_f16 v[10:13], v[66:69], v[234:237], v[10:13]
	v_mfma_f32_16x16x32_f16 v[6:9], v[74:77], v[234:237], v[6:9]
	v_mfma_f32_16x16x32_f16 v[62:65], v[70:73], v[166:169], v[62:65]
	v_mfma_f32_16x16x32_f16 v[58:61], v[78:81], v[166:169], v[58:61]
	v_mfma_f32_16x16x32_f16 v[46:49], v[70:73], v[222:225], v[46:49]
	v_mfma_f32_16x16x32_f16 v[38:41], v[78:81], v[222:225], v[38:41]
	v_mfma_f32_16x16x32_f16 v[30:33], v[70:73], v[230:233], v[30:33]
	v_mfma_f32_16x16x32_f16 v[22:25], v[78:81], v[230:233], v[22:25]
	v_mfma_f32_16x16x32_f16 v[10:13], v[70:73], v[238:241], v[10:13]
	v_mfma_f32_16x16x32_f16 v[6:9], v[78:81], v[238:241], v[6:9]
	s_setprio 0
	s_setprio 1
	v_mfma_f32_16x16x32_f16 v[54:57], v[82:85], v[162:165], v[54:57]
	v_mfma_f32_16x16x32_f16 v[50:53], v[90:93], v[162:165], v[50:53]
	v_mfma_f32_16x16x32_f16 v[42:45], v[82:85], v[194:197], v[42:45]
	v_mfma_f32_16x16x32_f16 v[34:37], v[90:93], v[194:197], v[34:37]
	v_mfma_f32_16x16x32_f16 v[26:29], v[82:85], v[226:229], v[26:29]
	v_mfma_f32_16x16x32_f16 v[18:21], v[90:93], v[226:229], v[18:21]
	v_mfma_f32_16x16x32_f16 v[14:17], v[82:85], v[234:237], v[14:17]
	v_mfma_f32_16x16x32_f16 v[2:5], v[90:93], v[234:237], v[2:5]
	v_mfma_f32_16x16x32_f16 v[54:57], v[86:89], v[166:169], v[54:57]
	v_mfma_f32_16x16x32_f16 v[50:53], v[94:97], v[166:169], v[50:53]
	v_mfma_f32_16x16x32_f16 v[42:45], v[86:89], v[222:225], v[42:45]
	v_mfma_f32_16x16x32_f16 v[34:37], v[94:97], v[222:225], v[34:37]
	v_mfma_f32_16x16x32_f16 v[26:29], v[86:89], v[230:233], v[26:29]
	v_mfma_f32_16x16x32_f16 v[18:21], v[94:97], v[230:233], v[18:21]
	v_mfma_f32_16x16x32_f16 v[14:17], v[86:89], v[238:241], v[14:17]
	v_mfma_f32_16x16x32_f16 v[2:5], v[94:97], v[238:241], v[2:5]
	s_setprio 0
	s_barrier
	s_add_i32 s33, 0, 0x18000
	s_add_i32 s92, 0, 0x1c000
	v_add_u32_e32 v78, s33, v208
	v_add_u32_e32 v94, s92, v208
	ds_read_b128 v[66:69], v78
	ds_read_b128 v[70:73], v78 offset:1024
	ds_read_b128 v[74:77], v78 offset:2048
	ds_read_b128 v[78:81], v78 offset:3072
	ds_read_b128 v[82:85], v94
	ds_read_b128 v[86:89], v94 offset:1024
	ds_read_b128 v[90:93], v94 offset:2048
	ds_read_b128 v[94:97], v94 offset:3072
	s_add_u32 s58, s58, 0x40000
	s_addc_u32 s59, s59, 0
	s_mov_b32 m0, s74
	v_lshl_add_u64 v[250:251], s[58:59], 0, v[180:181]
	ds_read_b128 v[162:165], v220 offset:32768
	ds_read_b128 v[166:169], v220 offset:33792
	ds_read_b128 v[194:197], v220 offset:34816
	ds_read_b128 v[222:225], v220 offset:35840
	ds_read_b128 v[226:229], v220 offset:36864
	ds_read_b128 v[230:233], v220 offset:37888
	ds_read_b128 v[234:237], v220 offset:38912
	ds_read_b128 v[238:241], v220 offset:39936
	global_load_lds_dwordx4 v[250:251], off
	v_lshl_add_u64 v[250:251], s[58:59], 0, v[182:183]
	s_mov_b32 m0, s75
	s_nop 0
	global_load_lds_dwordx4 v[250:251], off
	s_waitcnt vmcnt(8)
	s_waitcnt lgkmcnt(0)
	s_barrier
	s_setprio 1
	s_waitcnt lgkmcnt(0)
	v_mfma_f32_16x16x32_f16 v[158:161], v[66:69], v[162:165], v[158:161]
	v_mfma_f32_16x16x32_f16 v[154:157], v[74:77], v[162:165], v[154:157]
	v_mfma_f32_16x16x32_f16 v[142:145], v[66:69], v[194:197], v[142:145]
	v_mfma_f32_16x16x32_f16 v[134:137], v[74:77], v[194:197], v[134:137]
	v_mfma_f32_16x16x32_f16 v[126:129], v[66:69], v[226:229], v[126:129]
	v_mfma_f32_16x16x32_f16 v[118:121], v[74:77], v[226:229], v[118:121]
	v_mfma_f32_16x16x32_f16 v[106:109], v[66:69], v[234:237], v[106:109]
	v_mfma_f32_16x16x32_f16 v[102:105], v[74:77], v[234:237], v[102:105]
	v_mfma_f32_16x16x32_f16 v[158:161], v[70:73], v[166:169], v[158:161]
	v_mfma_f32_16x16x32_f16 v[154:157], v[78:81], v[166:169], v[154:157]
	v_mfma_f32_16x16x32_f16 v[142:145], v[70:73], v[222:225], v[142:145]
	v_mfma_f32_16x16x32_f16 v[134:137], v[78:81], v[222:225], v[134:137]
	v_mfma_f32_16x16x32_f16 v[126:129], v[70:73], v[230:233], v[126:129]
	v_mfma_f32_16x16x32_f16 v[118:121], v[78:81], v[230:233], v[118:121]
	v_mfma_f32_16x16x32_f16 v[106:109], v[70:73], v[238:241], v[106:109]
	v_mfma_f32_16x16x32_f16 v[102:105], v[78:81], v[238:241], v[102:105]
	s_setprio 0
	s_setprio 1
	v_mfma_f32_16x16x32_f16 v[150:153], v[82:85], v[162:165], v[150:153]
	v_mfma_f32_16x16x32_f16 v[146:149], v[90:93], v[162:165], v[146:149]
	v_mfma_f32_16x16x32_f16 v[138:141], v[82:85], v[194:197], v[138:141]
	v_mfma_f32_16x16x32_f16 v[130:133], v[90:93], v[194:197], v[130:133]
	v_mfma_f32_16x16x32_f16 v[122:125], v[82:85], v[226:229], v[122:125]
	v_mfma_f32_16x16x32_f16 v[114:117], v[90:93], v[226:229], v[114:117]
	v_mfma_f32_16x16x32_f16 v[110:113], v[82:85], v[234:237], v[110:113]
	v_mfma_f32_16x16x32_f16 v[98:101], v[90:93], v[234:237], v[98:101]
	v_mfma_f32_16x16x32_f16 v[150:153], v[86:89], v[166:169], v[150:153]
	v_mfma_f32_16x16x32_f16 v[146:149], v[94:97], v[166:169], v[146:149]
	v_mfma_f32_16x16x32_f16 v[138:141], v[86:89], v[222:225], v[138:141]
	v_mfma_f32_16x16x32_f16 v[130:133], v[94:97], v[222:225], v[130:133]
	v_mfma_f32_16x16x32_f16 v[122:125], v[86:89], v[230:233], v[122:125]
	v_mfma_f32_16x16x32_f16 v[114:117], v[94:97], v[230:233], v[114:117]
	v_mfma_f32_16x16x32_f16 v[110:113], v[86:89], v[238:241], v[110:113]
	v_mfma_f32_16x16x32_f16 v[98:101], v[94:97], v[238:241], v[98:101]
	s_setprio 0
	s_barrier
; #define PG8_LAS __attribute__((address_space(3)))
; #define PG8_STAGE(bufoff, gbase, voff) do { _Pragma("unroll") for (int _i = 0; _i < 2; ++_i) \
;         __builtin_amdgcn_global_load_lds((const unsigned*)((const char*)(gbase) + (voff)[_i]), (PG8_LAS unsigned*)(lds + (bufoff) + ldsw + _i * 8192), 16, 0, 0); } while (0)
; #define PG8_WAIT_V(n) asm volatile("s_waitcnt vmcnt(" #n ")" ::: "memory")
; #define PG8_BAR __builtin_amdgcn_s_barrier()
;     __device__ __forceinline__ void operator()(const f32x4 (&acc)[2][2][4][2], const Unit& u, int wr, int wc, int fr, int fq, PG8_LAS unsigned char* lds) const {
;         PG8_LAS float* halo = (PG8_LAS float*)(lds + STAGE_BYTES);
;         const int lane = fq * 16 + fr;
;         const int j0 = u.pn * 128 + wc * 32 + 8 * fq;
; #pragma unroll
;         for (int ai = 0; ai < 2; ++ai)
;             if (fr >= 14) { PG8_LAS float* h = halo + ((((ai * 2 + wr) * 4 + wc) * 2 + (fr - 14)) * 32 + fq * 8);
;                 *(PG8_LAS f32x4*)h = acc[ai][0][3][0]; *(PG8_LAS f32x4*)(h + 4) = acc[ai][0][3][1]; }
;         asm volatile("s_waitcnt lgkmcnt(0)" ::: "memory"); __builtin_amdgcn_s_barrier(); asm volatile("" ::: "memory");
;         float w0[8], w1[8], w2[8], bb[8];
;         { const f32x4 a0 = *(const f32x4*)(cw + j0), a1 = *(const f32x4*)(cw + j0 + 4), b0 = *(const f32x4*)(cw + DFF + j0), b1 = *(const f32x4*)(cw + DFF + j0 + 4);
;           const f32x4 c0 = *(const f32x4*)(cw + 2 * DFF + j0), c1 = *(const f32x4*)(cw + 2 * DFF + j0 + 4), d0 = *(const f32x4*)(cb + j0), d1 = *(const f32x4*)(cb + j0 + 4);
; template <class Epi>
; __device__ __forceinline__ void gemm_phase(PG8_LAS unsigned char* lds, const Gemm g, const StaticOrder& S_, const Epi& E) {
;     ...
;             PG8_WAIT_V(8); PG8_WAIT_L(0); PG8_BAR; PG8_MMA(1, 0, At, B0); PG8_MMA(1, 1, At, B1); PG8_BAR; PG8_SCHED;
;             PG8_LDB(B0, 1, 0); PG8_LDB(B1, 1, 1); PG8_SCHED; PG8_LDA(At, 1, 0); PG8_STAGE(PG8_SA(0, 1), a2 + hstepA, voffA);
;             PG8_WAIT_V(8); PG8_WAIT_L(0); PG8_BAR; PG8_MMA(0, 0, At, B0); PG8_MMA(0, 1, At, B1); PG8_BAR; PG8_SCHED;
;             PG8_LDA(At, 1, 1); PG8_STAGE(PG8_SB(1, 0), b3, voffB); PG8_STAGE(PG8_SB(1, 1), b3 + hstepB, voffB); PG8_STAGE(PG8_SA(1, 0), a3, voffA);
;             PG8_WAIT_V(8); PG8_WAIT_L(0); PG8_BAR; PG8_MMA(1, 0, At, B0); PG8_MMA(1, 1, At, B1); PG8_BAR; PG8_SCHED;
;         }
;         if (wr == 0) PG8_BAR;
	s_add_i32 s33, s33, s71
	v_lshl_add_u64 v[242:243], v[242:243], 0, s[86:87]
	s_mov_b32 m0, s33
	ds_read_b128 v[162:165], v220 offset:49152
	ds_read_b128 v[166:169], v220 offset:50176
	ds_read_b128 v[194:197], v220 offset:51200
	ds_read_b128 v[222:225], v220 offset:52224
	ds_read_b128 v[226:229], v220 offset:53248
	ds_read_b128 v[230:233], v220 offset:54272
	ds_read_b128 v[234:237], v220 offset:55296
	ds_read_b128 v[238:241], v220 offset:56320
	global_load_lds_dwordx4 v[242:243], off
	s_add_i32 m0, s33, 0x2000
	s_add_u32 s2, s2, 0x40080
	v_lshl_add_u64 v[242:243], v[244:245], 0, s[86:87]
	s_addc_u32 s3, s3, 0
	s_add_i32 s33, s92, s71
	global_load_lds_dwordx4 v[242:243], off
	v_lshl_add_u64 v[242:243], s[2:3], 0, v[0:1]
	s_mov_b32 m0, s33
	s_nop 0
	global_load_lds_dwordx4 v[242:243], off
	v_lshl_add_u64 v[242:243], s[2:3], 0, v[184:185]
	s_add_i32 m0, s33, 0x2000
	s_nop 0
	global_load_lds_dwordx4 v[242:243], off
	v_lshl_add_u64 v[242:243], v[246:247], 0, s[86:87]
	s_mov_b32 m0, s77
	s_nop 0
	global_load_lds_dwordx4 v[242:243], off
	v_lshl_add_u64 v[242:243], v[248:249], 0, s[86:87]
	s_mov_b32 m0, s78
	s_nop 0
	global_load_lds_dwordx4 v[242:243], off
	s_waitcnt vmcnt(8)
	s_waitcnt lgkmcnt(0)
	s_barrier
	s_setprio 1
	s_waitcnt lgkmcnt(0)
	v_mfma_f32_16x16x32_f16 v[62:65], v[66:69], v[162:165], v[62:65]
	v_mfma_f32_16x16x32_f16 v[58:61], v[74:77], v[162:165], v[58:61]
	v_mfma_f32_16x16x32_f16 v[46:49], v[66:69], v[194:197], v[46:49]
	v_mfma_f32_16x16x32_f16 v[38:41], v[74:77], v[194:197], v[38:41]
	v_mfma_f32_16x16x32_f16 v[30:33], v[66:69], v[226:229], v[30:33]
	v_mfma_f32_16x16x32_f16 v[22:25], v[74:77], v[226:229], v[22:25]
	v_mfma_f32_16x16x32_f16 v[10:13], v[66:69], v[234:237], v[10:13]
	v_mfma_f32_16x16x32_f16 v[6:9], v[74:77], v[234:237], v[6:9]
	v_mfma_f32_16x16x32_f16 v[62:65], v[70:73], v[166:169], v[62:65]
	v_mfma_f32_16x16x32_f16 v[58:61], v[78:81], v[166:169], v[58:61]
	v_mfma_f32_16x16x32_f16 v[46:49], v[70:73], v[222:225], v[46:49]
	v_mfma_f32_16x16x32_f16 v[38:41], v[78:81], v[222:225], v[38:41]
	v_mfma_f32_16x16x32_f16 v[30:33], v[70:73], v[230:233], v[30:33]
	v_mfma_f32_16x16x32_f16 v[22:25], v[78:81], v[230:233], v[22:25]
	v_mfma_f32_16x16x32_f16 v[10:13], v[70:73], v[238:241], v[10:13]
	v_mfma_f32_16x16x32_f16 v[6:9], v[78:81], v[238:241], v[6:9]
	s_setprio 0
	s_setprio 1
	v_mfma_f32_16x16x32_f16 v[54:57], v[82:85], v[162:165], v[54:57]
	v_mfma_f32_16x16x32_f16 v[50:53], v[90:93], v[162:165], v[50:53]
	v_mfma_f32_16x16x32_f16 v[42:45], v[82:85], v[194:197], v[42:45]
	v_mfma_f32_16x16x32_f16 v[34:37], v[90:93], v[194:197], v[34:37]
	v_mfma_f32_16x16x32_f16 v[26:29], v[82:85], v[226:229], v[26:29]
	v_mfma_f32_16x16x32_f16 v[18:21], v[90:93], v[226:229], v[18:21]
	v_mfma_f32_16x16x32_f16 v[14:17], v[82:85], v[234:237], v[14:17]
	v_mfma_f32_16x16x32_f16 v[2:5], v[90:93], v[234:237], v[2:5]
	v_mfma_f32_16x16x32_f16 v[54:57], v[86:89], v[166:169], v[54:57]
	v_mfma_f32_16x16x32_f16 v[50:53], v[94:97], v[166:169], v[50:53]
	v_mfma_f32_16x16x32_f16 v[42:45], v[86:89], v[222:225], v[42:45]
	v_mfma_f32_16x16x32_f16 v[34:37], v[94:97], v[222:225], v[34:37]
	v_mfma_f32_16x16x32_f16 v[26:29], v[86:89], v[230:233], v[26:29]
	v_mfma_f32_16x16x32_f16 v[18:21], v[94:97], v[230:233], v[18:21]
	v_mfma_f32_16x16x32_f16 v[14:17], v[86:89], v[238:241], v[14:17]
	v_mfma_f32_16x16x32_f16 v[2:5], v[94:97], v[238:241], v[2:5]
	s_setprio 0
	s_barrier
	s_add_i32 s88, s88, 2
	s_add_u32 s83, s83, 0x100
	s_addc_u32 s84, s84, 0
	s_add_u32 s56, s56, 0x100
	s_addc_u32 s57, s57, 0
	s_cmp_gt_u32 s88, 13
	s_cbranch_scc0 .LBB0_1307
	v_lshl_or_b32 v194, s54, 7, v219
	v_ashrrev_i32_e32 v195, 31, v194
	v_lshlrev_b64 v[196:197], 2, v[194:195]
	v_lshl_add_u64 v[70:71], s[16:17], 0, v[196:197]
	v_lshl_add_u64 v[74:75], s[40:41], 0, v[196:197]
	v_lshl_add_u64 v[78:79], s[42:43], 0, v[196:197]
	v_lshl_add_u64 v[94:95], s[18:19], 0, v[196:197]
	global_load_dwordx4 v[66:69], v[70:71], off offset:16
	global_load_dwordx4 v[82:85], v[70:71], off
	s_nop 0
	global_load_dwordx4 v[70:73], v[74:75], off offset:16
	global_load_dwordx4 v[86:89], v[74:75], off
	s_nop 0
	global_load_dwordx4 v[74:77], v[78:79], off offset:16
	global_load_dwordx4 v[90:93], v[78:79], off
	s_nop 0
	global_load_dwordx4 v[78:81], v[94:95], off offset:16
	s_nop 0
	global_load_dwordx4 v[94:97], v[94:95], off
	s_and_b64 vcc, exec, s[24:25]
	s_cbranch_vccz .LBB0_1310
	s_barrier

; #define PG8_LAS __attribute__((address_space(3)))
;     __device__ __forceinline__ void operator()(const f32x4 (&acc)[2][2][4][2], const Unit& u, int wr, int wc, int fr, int fq, PG8_LAS unsigned char* lds) const {
;     ...
;         asm volatile("s_waitcnt lgkmcnt(0)" ::: "memory"); __builtin_amdgcn_s_barrier(); asm volatile("" ::: "memory");
;     ...
;             if (G > 0) {
;                 PG8_LAS float* h = halo + ((((G - 1) * 4 + wc) * 2) * 32 + fq * 8);
;                 const f32x4 r62a = *(PG8_LAS f32x4*)h, r62b = *(PG8_LAS f32x4*)(h + 4), r63a = *(PG8_LAS f32x4*)(h + 32), r63b = *(PG8_LAS f32x4*)(h + 36);
; #pragma unroll
;                 for (int j = 0; j < 4; ++j) { p1[j] = r63a[j]; p1[4 + j] = r63b[j]; p2[j] = fr == 0 ? r62a[j] : r63a[j]; p2[4 + j] = fr == 0 ? r62b[j] : r63b[j]; }
.LBB0_1312:
	s_or_b64 exec, exec, s[2:3]
	s_waitcnt lgkmcnt(0)
	s_barrier
	s_andn2_b64 vcc, exec, s[26:27]
	s_cbranch_vccnz .LBB0_1314
	ds_read_b128 v[222:225], v211
	ds_read_b128 v[226:229], v212
	ds_read_b128 v[162:165], v213
	ds_read_b128 v[166:169], v214
	s_waitcnt lgkmcnt(0)
	v_cndmask_b32_e64 v238, v162, v222, s[6:7]
	v_cndmask_b32_e64 v242, v166, v226, s[6:7]
	v_cndmask_b32_e64 v239, v163, v223, s[6:7]
	v_cndmask_b32_e64 v243, v167, v227, s[6:7]
	v_cndmask_b32_e64 v240, v164, v224, s[6:7]
	v_cndmask_b32_e64 v244, v168, v228, s[6:7]
	v_cndmask_b32_e64 v241, v165, v225, s[6:7]
	v_cndmask_b32_e64 v245, v169, v229, s[6:7]
	s_branch .LBB0_1315
